# stick-breaking attention QK segment as one continuous 16-MFMA segment (second chain's K fragments read while the first chain runs)
# baseline (speedup 1.0000x reference)
.LBB0_41:
	s_add_i32 s0, s42, -1
	v_cmp_le_i32_e32 vcc, s2, v198
	s_and_b32 s45, s0, 1
	s_cbranch_vccnz .LBB0_44
	v_cmp_gt_f32_e32 vcc, s58, v172
	s_cmp_eq_u64 vcc, exec
	s_cbranch_scc1 .LBB0_44
	s_mul_i32 s0, s45, 0x8c00
	s_add_i32 s0, s0, 0
	v_add_u32_e32 v0, s0, v189
	v_add_u32_e32 v173, v0, v188
	ds_read_b128 v[174:177], v173 offset:8704
	ds_read_b128 v[200:203], v173 offset:8736
	ds_read_b128 v[204:207], v173 offset:8768
	ds_read_b128 v[208:211], v173 offset:8800
	ds_read_b128 v[212:215], v173 offset:8832
	ds_read_b128 v[216:219], v173 offset:8864
	ds_read_b128 v[220:223], v173 offset:8896
	ds_read_b128 v[224:227], v173 offset:8928
	s_setprio 1
	s_waitcnt lgkmcnt(7)
	v_mfma_f32_32x32x16_bf16 v[82:97], v[174:177], v[98:101], 0
	ds_read_b128 v[174:177], v173
	s_waitcnt lgkmcnt(7)
	v_mfma_f32_32x32x16_bf16 v[82:97], v[200:203], v[102:105], v[82:97]
	ds_read_b128 v[200:203], v173 offset:32
	s_waitcnt lgkmcnt(7)
	v_mfma_f32_32x32x16_bf16 v[82:97], v[204:207], v[106:109], v[82:97]
	ds_read_b128 v[204:207], v173 offset:64
	s_waitcnt lgkmcnt(7)
	v_mfma_f32_32x32x16_bf16 v[82:97], v[208:211], v[110:113], v[82:97]
	ds_read_b128 v[208:211], v173 offset:96
	s_waitcnt lgkmcnt(7)
	v_mfma_f32_32x32x16_bf16 v[82:97], v[212:215], v[114:117], v[82:97]
	ds_read_b128 v[212:215], v173 offset:128
	s_waitcnt lgkmcnt(7)
	v_mfma_f32_32x32x16_bf16 v[82:97], v[216:219], v[118:121], v[82:97]
	ds_read_b128 v[216:219], v173 offset:160
	s_waitcnt lgkmcnt(7)
	v_mfma_f32_32x32x16_bf16 v[82:97], v[220:223], v[122:125], v[82:97]
	ds_read_b128 v[220:223], v173 offset:192
	s_waitcnt lgkmcnt(7)
	v_mfma_f32_32x32x16_bf16 v[82:97], v[224:227], v[126:129], v[82:97]
	ds_read_b128 v[224:227], v173 offset:224
	s_waitcnt lgkmcnt(7)
	v_mfma_f32_32x32x16_bf16 v[66:81], v[174:177], v[98:101], 0
	s_waitcnt lgkmcnt(6)
	v_mfma_f32_32x32x16_bf16 v[66:81], v[200:203], v[102:105], v[66:81]
	s_waitcnt lgkmcnt(5)
	v_mfma_f32_32x32x16_bf16 v[66:81], v[204:207], v[106:109], v[66:81]
	s_waitcnt lgkmcnt(4)
	v_mfma_f32_32x32x16_bf16 v[66:81], v[208:211], v[110:113], v[66:81]
	s_waitcnt lgkmcnt(3)
	v_mfma_f32_32x32x16_bf16 v[66:81], v[212:215], v[114:117], v[66:81]
	s_waitcnt lgkmcnt(2)
	v_mfma_f32_32x32x16_bf16 v[66:81], v[216:219], v[118:121], v[66:81]
	s_waitcnt lgkmcnt(1)
	v_mfma_f32_32x32x16_bf16 v[66:81], v[220:223], v[122:125], v[66:81]
	s_waitcnt lgkmcnt(0)
	v_mfma_f32_32x32x16_bf16 v[66:81], v[224:227], v[126:129], v[66:81]
	s_setprio 0
	s_nop 10
	v_mov_b32_e32 v236, 1.0
	v_cndmask_b32_e64 v173, 0, 1.0, s[4:5]
	v_cmp_gt_i32_e32 vcc, 28, v159
	s_cmp_eq_u64 vcc, 0
	s_cbranch_scc1 .Lstk_nm1
	v_cmp_lt_i32_e64 s[0:1], 0, v159
	v_cmp_lt_i32_e64 s[8:9], 1, v159
	v_cmp_lt_i32_e64 s[10:11], 2, v159
	v_cmp_lt_i32_e64 s[12:13], 3, v159
	v_cndmask_b32_e64 v82, v231, v82, s[0:1]
	v_cndmask_b32_e64 v83, v231, v83, s[8:9]
	v_cndmask_b32_e64 v84, v231, v84, s[10:11]
	v_cndmask_b32_e64 v85, v231, v85, s[12:13]
	v_cmp_lt_i32_e64 s[0:1], 8, v159
	v_cmp_lt_i32_e64 s[8:9], 9, v159
	v_cmp_lt_i32_e64 s[10:11], 10, v159
	v_cmp_lt_i32_e64 s[12:13], 11, v159
	v_cndmask_b32_e64 v86, v231, v86, s[0:1]
	v_cndmask_b32_e64 v87, v231, v87, s[8:9]
	v_cndmask_b32_e64 v88, v231, v88, s[10:11]
	v_cndmask_b32_e64 v89, v231, v89, s[12:13]
	v_cmp_lt_i32_e64 s[0:1], 16, v159
	v_cmp_lt_i32_e64 s[8:9], 17, v159
	v_cmp_lt_i32_e64 s[10:11], 18, v159
	v_cmp_lt_i32_e64 s[12:13], 19, v159
	v_cndmask_b32_e64 v90, v231, v90, s[0:1]
	v_cndmask_b32_e64 v91, v231, v91, s[8:9]
	v_cndmask_b32_e64 v92, v231, v92, s[10:11]
	v_cndmask_b32_e64 v93, v231, v93, s[12:13]
	v_cmp_lt_i32_e64 s[0:1], 24, v159
	v_cmp_lt_i32_e64 s[8:9], 25, v159
	v_cmp_lt_i32_e64 s[10:11], 26, v159
	v_cmp_lt_i32_e64 s[12:13], 27, v159
	v_cndmask_b32_e64 v94, v231, v94, s[0:1]
	v_cndmask_b32_e64 v95, v231, v95, s[8:9]
	v_cndmask_b32_e64 v96, v231, v96, s[10:11]
	v_cndmask_b32_e64 v97, v231, v97, s[12:13]
